# attention: lane-pair max exchange only in the rescale path, one common-path threshold check for both blocks, last QK MFMA hoisted (no pad nops)
# speedup vs baseline: 1.0028x; 1.0015x over previous
; #define MFMA32(a, b, c) __builtin_amdgcn_mfma_f32_32x32x16_bf16((a), (b), (c), 0, 0, 0)
; __device__ __forceinline__ void attn_unit2(const bf16_t* Qm, const bf16_t* KVm, const bf16_t* P1, bf16_t* OP, int q0, int h, int klat, int nlat, int kctx, int nt, uchar* lds, bool nostore = false) {
;     ...
;         f32x16 sA0 = {}, sA1 = {}, sB0 = {}, sB1 = {};
;         { const uchar* kb = Kt + buf * KT_BYTES + l32 * KROW + hi * 16;
; #pragma unroll
;           for (int s = 0; s < 6; ++s) { const bf16x8 a0 = *(const bf16x8*)(kb + s * 32), a1 = *(const bf16x8*)(kb + 32 * KROW + s * 32);
;               sA0 = MFMA32(a0, qa[s], sA0); sA1 = MFMA32(a1, qa[s], sA1); sB0 = MFMA32(a0, qb[s], sB0); sB1 = MFMA32(a1, qb[s], sB1); } }
.LBB0_1117:
	s_and_b32 s4, s9, 1
	s_mul_i32 s5, s4, 0x3400
	v_add_u32_e32 v0, s5, v226
	ds_read_b128 v[246:249], v0 offset:176
	ds_read_b128 v[66:69], v0
	ds_read_b128 v[70:73], v0 offset:32
	ds_read_b128 v[74:77], v0 offset:6656
	ds_read_b128 v[234:237], v0 offset:6688
	ds_read_b128 v[208:211], v0 offset:6832
	s_waitcnt lgkmcnt(5)
	v_mfma_f32_32x32x16_bf16 v[114:129], v[246:249], v[216:219], 0
	v_mfma_f32_32x32x16_bf16 v[98:113], v[246:249], v[190:193], 0
	s_waitcnt lgkmcnt(4)
	v_mfma_f32_32x32x16_bf16 v[114:129], v[66:69], v[130:133], v[114:129]
	v_mfma_f32_32x32x16_bf16 v[98:113], v[66:69], v[170:173], v[98:113]
	s_waitcnt lgkmcnt(3)
	v_mfma_f32_32x32x16_bf16 v[114:129], v[70:73], v[134:137], v[114:129]
	v_mfma_f32_32x32x16_bf16 v[98:113], v[70:73], v[138:141], v[98:113]
	ds_read_b128 v[66:69], v0 offset:64
	ds_read_b128 v[70:73], v0 offset:96
	ds_read_b128 v[238:241], v0 offset:6720
	ds_read_b128 v[242:245], v0 offset:6752
	s_waitcnt lgkmcnt(3)
	v_mfma_f32_32x32x16_bf16 v[114:129], v[66:69], v[146:149], v[114:129]
	v_mfma_f32_32x32x16_bf16 v[98:113], v[66:69], v[142:145], v[98:113]
	v_mfma_f32_32x32x16_bf16 v[82:97], v[208:211], v[216:219], 0
	v_mfma_f32_32x32x16_bf16 v[82:97], v[74:77], v[130:133], v[82:97]
	s_waitcnt lgkmcnt(2)
	v_mfma_f32_32x32x16_bf16 v[114:129], v[70:73], v[150:153], v[114:129]
	v_mfma_f32_32x32x16_bf16 v[98:113], v[70:73], v[154:157], v[98:113]
	ds_read_b128 v[66:69], v0 offset:128
	ds_read_b128 v[70:73], v0 offset:160
	ds_read_b128 v[246:249], v0 offset:6784
	ds_read_b128 v[212:215], v0 offset:6816
	v_mfma_f32_32x32x16_bf16 v[82:97], v[234:237], v[134:137], v[82:97]
	s_waitcnt lgkmcnt(3)
	v_mfma_f32_32x32x16_bf16 v[114:129], v[66:69], v[162:165], v[114:129]
	v_mfma_f32_32x32x16_bf16 v[98:113], v[66:69], v[158:161], v[98:113]
	v_mfma_f32_32x32x16_bf16 v[82:97], v[238:241], v[146:149], v[82:97]
	s_waitcnt lgkmcnt(2)
	v_mfma_f32_32x32x16_bf16 v[114:129], v[70:73], v[166:169], v[114:129]
	v_mfma_f32_32x32x16_bf16 v[98:113], v[70:73], v[174:177], v[98:113]
	s_nop 10
	v_max_f32_e32 v0, v115, v115
	v_mfma_f32_32x32x16_bf16 v[66:81], v[74:77], v[170:173], 0
	v_mfma_f32_32x32x16_bf16 v[66:81], v[208:211], v[190:193], v[66:81]
	v_mfma_f32_32x32x16_bf16 v[82:97], v[242:245], v[150:153], v[82:97]
	v_mfma_f32_32x32x16_bf16 v[66:81], v[234:237], v[138:141], v[66:81]
	v_max_f32_e32 v234, v114, v114
	v_max_f32_e32 v0, v234, v0
	s_waitcnt lgkmcnt(1)
	v_mfma_f32_32x32x16_bf16 v[82:97], v[246:249], v[162:165], v[82:97]
	v_mfma_f32_32x32x16_bf16 v[66:81], v[238:241], v[142:145], v[66:81]
	s_waitcnt lgkmcnt(0)
	v_mfma_f32_32x32x16_bf16 v[82:97], v[212:215], v[166:169], v[82:97]
	v_mfma_f32_32x32x16_bf16 v[66:81], v[242:245], v[154:157], v[66:81]
	s_nop 10
	v_max3_f32 v234, v116, v117, v83
	v_max3_f32 v0, v0, v82, v84
	v_max3_f32 v0, v0, v85, v118
	v_max3_f32 v234, v234, v120, v121
	v_max3_f32 v0, v0, v119, v86
	v_max3_f32 v234, v234, v88, v89
	v_max3_f32 v0, v0, v87, v122
	v_mfma_f32_32x32x16_bf16 v[66:81], v[246:249], v[158:161], v[66:81]
	v_mfma_f32_32x32x16_bf16 v[66:81], v[212:215], v[174:177], v[66:81]
	v_max3_f32 v234, v234, v124, v125
	v_max3_f32 v0, v0, v123, v90
	v_max3_f32 v234, v234, v92, v93
	v_max3_f32 v0, v0, v91, v126
	v_max3_f32 v234, v234, v128, v129
	v_max3_f32 v0, v0, v127, v94
	v_max3_f32 v234, v234, v96, v97
	v_max3_f32 v0, v0, v95, v234
	v_max3_f32 v235, v98, v99, v100
	v_max3_f32 v236, v101, v102, v103
	v_max3_f32 v235, v235, v104, v105
	v_max3_f32 v236, v236, v106, v107
	v_max3_f32 v235, v235, v108, v109
	v_max3_f32 v236, v236, v110, v111
	v_max3_f32 v235, v235, v112, v113
	v_max3_f32 v236, v236, v66, v67
	v_max3_f32 v235, v235, v68, v69
	v_max3_f32 v236, v236, v70, v71
	v_max3_f32 v235, v235, v72, v73
	v_max3_f32 v236, v236, v74, v75
	v_max3_f32 v235, v235, v76, v77
	v_max3_f32 v236, v236, v78, v79
	v_max3_f32 v235, v235, v80, v81
	v_max_f32_e32 v235, v235, v236
	v_max_f32_e32 v236, v0, v235
	v_cmp_lt_f32_e32 vcc, 0x41000000, v236
	s_cmp_eq_u32 s9, 0
	s_cbranch_scc1 .Latt_rare
	s_cbranch_vccz .LBB0_1121
.Latt_rare:
	ds_bpermute_b32 v234, v227, v0
	ds_bpermute_b32 v236, v227, v235
	s_waitcnt lgkmcnt(0)
	v_max_f32_e32 v0, v0, v234
	v_max_f32_e32 v235, v235, v236

.LBB0_1119:
	v_mov_b32_e32 v0, v235
